# panel barriers guarded on the 256-workgroup grid (fallback to grid barrier otherwise); otherwise same as previous best
# baseline (speedup 1.0000x reference)
.LBB0_571:
	s_cmp_ge_i32 s70, s71
	s_mov_b64 s[2:3], -1
	s_cbranch_scc1 .LBB0_23
	s_cmp_lg_u32 s34, 0x100
	s_cbranch_scc1 .LBB0_580
	s_cmp_eq_u32 s70, 5
	s_cbranch_scc1 .Lpb_entry
	s_cmp_eq_u32 s70, 6
	s_cbranch_scc1 .Lpb_entry
	s_cmp_eq_u32 s70, 12
	s_cbranch_scc1 .Lpb_entry
	s_cmp_eq_u32 s70, 13
	s_cbranch_scc1 .Lpb_entry
	s_branch .LBB0_580
